# attention loop: running-max subtraction as 16 packed adds with neg modifiers instead of 32 scalar subs (bit-identical)
# speedup vs baseline: 1.0158x; 1.0026x over previous
.Lq1_body:
	global_load_dwordx4 v[28:31], v202, s[100:101] offset:-128
	global_load_dwordx4 v[32:35], v202, s[100:101]
	global_load_dwordx4 v[4:7], v203, s[100:101] offset:-128
	global_load_dwordx4 v[12:15], v203, s[100:101]
	ds_read_b128 v[44:47], v214 offset:35840
	ds_read_b128 v[72:75], v214 offset:35904
	ds_read_b128 v[92:95], v214 offset:40192
	ds_read_b128 v[112:115], v214 offset:40256
	ds_read_b128 v[132:135], v214 offset:44544
	ds_read_b128 v[148:151], v214 offset:44608
	ds_read_b128 v[136:139], v214 offset:48896
	ds_read_b128 v[152:155], v214 offset:48960
	s_waitcnt lgkmcnt(7)
	v_mfma_f32_16x16x32_bf16 v[140:143], v[44:47], v[8:11], 0
	v_mfma_f32_16x16x32_bf16 v[44:47], v[44:47], v[20:23], 0
	s_waitcnt lgkmcnt(1)
	v_mfma_f32_16x16x32_bf16 v[156:159], v[92:95], v[8:11], 0
	v_mfma_f32_16x16x32_bf16 v[92:95], v[92:95], v[20:23], 0
	v_mfma_f32_16x16x32_bf16 v[160:163], v[132:135], v[8:11], 0
	v_mfma_f32_16x16x32_bf16 v[132:135], v[132:135], v[20:23], 0
	v_mfma_f32_16x16x32_bf16 v[164:167], v[136:139], v[8:11], 0
	v_mfma_f32_16x16x32_bf16 v[168:171], v[136:139], v[20:23], 0
	v_mfma_f32_16x16x32_bf16 v[144:147], v[72:75], v[16:19], v[140:143]
	v_mfma_f32_16x16x32_bf16 v[136:139], v[72:75], v[24:27], v[44:47]
	v_mfma_f32_16x16x32_bf16 v[44:47], v[112:115], v[16:19], v[156:159]
	v_mfma_f32_16x16x32_bf16 v[92:95], v[112:115], v[24:27], v[92:95]
	v_mfma_f32_16x16x32_bf16 v[140:143], v[148:151], v[16:19], v[160:163]
	v_mfma_f32_16x16x32_bf16 v[132:135], v[148:151], v[24:27], v[132:135]
	s_waitcnt lgkmcnt(0)
	v_mfma_f32_16x16x32_bf16 v[72:75], v[152:155], v[16:19], v[164:167]
	v_mfma_f32_16x16x32_bf16 v[112:115], v[152:155], v[24:27], v[168:171]
	s_cmp_eq_u32 s98, 0
	s_cbranch_scc1 .LBB0_859
	v_pk_add_f32 v[146:147], v[146:147], v[196:197] op_sel_hi:[1,0] neg_lo:[0,1] neg_hi:[0,1]
	v_pk_add_f32 v[144:145], v[144:145], v[196:197] op_sel_hi:[1,0] neg_lo:[0,1] neg_hi:[0,1]
	v_pk_add_f32 v[46:47], v[46:47], v[196:197] op_sel_hi:[1,0] neg_lo:[0,1] neg_hi:[0,1]
	v_pk_add_f32 v[44:45], v[44:45], v[196:197] op_sel_hi:[1,0] neg_lo:[0,1] neg_hi:[0,1]
	v_pk_add_f32 v[142:143], v[142:143], v[196:197] op_sel_hi:[1,0] neg_lo:[0,1] neg_hi:[0,1]
	v_pk_add_f32 v[140:141], v[140:141], v[196:197] op_sel_hi:[1,0] neg_lo:[0,1] neg_hi:[0,1]
	v_pk_add_f32 v[74:75], v[74:75], v[196:197] op_sel_hi:[1,0] neg_lo:[0,1] neg_hi:[0,1]
	v_pk_add_f32 v[72:73], v[72:73], v[196:197] op_sel_hi:[1,0] neg_lo:[0,1] neg_hi:[0,1]
	v_pk_add_f32 v[138:139], v[138:139], v[196:197] op_sel:[0,1] op_sel_hi:[1,1] neg_lo:[0,1] neg_hi:[0,1]
	v_pk_add_f32 v[136:137], v[136:137], v[196:197] op_sel:[0,1] op_sel_hi:[1,1] neg_lo:[0,1] neg_hi:[0,1]
	v_pk_add_f32 v[94:95], v[94:95], v[196:197] op_sel:[0,1] op_sel_hi:[1,1] neg_lo:[0,1] neg_hi:[0,1]
	v_pk_add_f32 v[92:93], v[92:93], v[196:197] op_sel:[0,1] op_sel_hi:[1,1] neg_lo:[0,1] neg_hi:[0,1]
	v_pk_add_f32 v[134:135], v[134:135], v[196:197] op_sel:[0,1] op_sel_hi:[1,1] neg_lo:[0,1] neg_hi:[0,1]
	v_pk_add_f32 v[132:133], v[132:133], v[196:197] op_sel:[0,1] op_sel_hi:[1,1] neg_lo:[0,1] neg_hi:[0,1]
	v_pk_add_f32 v[114:115], v[114:115], v[196:197] op_sel:[0,1] op_sel_hi:[1,1] neg_lo:[0,1] neg_hi:[0,1]
	v_pk_add_f32 v[112:113], v[112:113], v[196:197] op_sel:[0,1] op_sel_hi:[1,1] neg_lo:[0,1] neg_hi:[0,1]

.Lq1_h2_nok:
	global_load_dwordx4 v[4:7], v203, s[100:101] offset:-128
	global_load_dwordx4 v[12:15], v203, s[100:101]
	s_cmp_ge_u32 s89, s83
	s_cbranch_scc1 .Lq1_h2_pvonly
	ds_read_b128 v[36:39], v214
	ds_read_b128 v[40:43], v214 offset:64
	ds_read_b128 v[60:63], v214 offset:4352
	ds_read_b128 v[84:87], v214 offset:4416
	ds_read_b128 v[64:67], v214 offset:8704
	ds_read_b128 v[124:127], v214 offset:8768
	ds_read_b128 v[108:111], v214 offset:13056
	ds_read_b128 v[100:103], v214 offset:13120
	s_waitcnt lgkmcnt(7)
	v_mfma_f32_16x16x32_bf16 v[120:123], v[36:39], v[8:11], 0
	v_mfma_f32_16x16x32_bf16 v[36:39], v[36:39], v[20:23], 0
	s_waitcnt lgkmcnt(1)
	v_mfma_f32_16x16x32_bf16 v[116:119], v[60:63], v[8:11], 0
	v_mfma_f32_16x16x32_bf16 v[60:63], v[60:63], v[20:23], 0
	v_mfma_f32_16x16x32_bf16 v[96:99], v[64:67], v[8:11], 0
	v_mfma_f32_16x16x32_bf16 v[64:67], v[64:67], v[20:23], 0
	v_mfma_f32_16x16x32_bf16 v[104:107], v[108:111], v[8:11], 0
	v_mfma_f32_16x16x32_bf16 v[76:79], v[108:111], v[20:23], 0
	v_mfma_f32_16x16x32_bf16 v[128:131], v[40:43], v[16:19], v[120:123]
	v_mfma_f32_16x16x32_bf16 v[108:111], v[40:43], v[24:27], v[36:39]
	v_mfma_f32_16x16x32_bf16 v[36:39], v[84:87], v[16:19], v[116:119]
	v_mfma_f32_16x16x32_bf16 v[60:63], v[84:87], v[24:27], v[60:63]
	v_mfma_f32_16x16x32_bf16 v[120:123], v[124:127], v[16:19], v[96:99]
	v_mfma_f32_16x16x32_bf16 v[64:67], v[124:127], v[24:27], v[64:67]
	s_waitcnt lgkmcnt(0)
	v_mfma_f32_16x16x32_bf16 v[40:43], v[100:103], v[16:19], v[104:107]
	v_mfma_f32_16x16x32_bf16 v[84:87], v[100:103], v[24:27], v[76:79]
	s_cmp_eq_u32 s98, 0
	s_cbranch_scc1 .LBB0_875
	v_pk_add_f32 v[130:131], v[130:131], v[196:197] op_sel_hi:[1,0] neg_lo:[0,1] neg_hi:[0,1]
	v_pk_add_f32 v[128:129], v[128:129], v[196:197] op_sel_hi:[1,0] neg_lo:[0,1] neg_hi:[0,1]
	v_pk_add_f32 v[38:39], v[38:39], v[196:197] op_sel_hi:[1,0] neg_lo:[0,1] neg_hi:[0,1]
	v_pk_add_f32 v[36:37], v[36:37], v[196:197] op_sel_hi:[1,0] neg_lo:[0,1] neg_hi:[0,1]
	v_pk_add_f32 v[122:123], v[122:123], v[196:197] op_sel_hi:[1,0] neg_lo:[0,1] neg_hi:[0,1]
	v_pk_add_f32 v[120:121], v[120:121], v[196:197] op_sel_hi:[1,0] neg_lo:[0,1] neg_hi:[0,1]
	v_pk_add_f32 v[42:43], v[42:43], v[196:197] op_sel_hi:[1,0] neg_lo:[0,1] neg_hi:[0,1]
	v_pk_add_f32 v[40:41], v[40:41], v[196:197] op_sel_hi:[1,0] neg_lo:[0,1] neg_hi:[0,1]
	v_pk_add_f32 v[110:111], v[110:111], v[196:197] op_sel:[0,1] op_sel_hi:[1,1] neg_lo:[0,1] neg_hi:[0,1]
	v_pk_add_f32 v[108:109], v[108:109], v[196:197] op_sel:[0,1] op_sel_hi:[1,1] neg_lo:[0,1] neg_hi:[0,1]
	v_pk_add_f32 v[62:63], v[62:63], v[196:197] op_sel:[0,1] op_sel_hi:[1,1] neg_lo:[0,1] neg_hi:[0,1]
	v_pk_add_f32 v[60:61], v[60:61], v[196:197] op_sel:[0,1] op_sel_hi:[1,1] neg_lo:[0,1] neg_hi:[0,1]
	v_pk_add_f32 v[66:67], v[66:67], v[196:197] op_sel:[0,1] op_sel_hi:[1,1] neg_lo:[0,1] neg_hi:[0,1]
	v_pk_add_f32 v[64:65], v[64:65], v[196:197] op_sel:[0,1] op_sel_hi:[1,1] neg_lo:[0,1] neg_hi:[0,1]
	v_pk_add_f32 v[86:87], v[86:87], v[196:197] op_sel:[0,1] op_sel_hi:[1,1] neg_lo:[0,1] neg_hi:[0,1]
	v_pk_add_f32 v[84:85], v[84:85], v[196:197] op_sel:[0,1] op_sel_hi:[1,1] neg_lo:[0,1] neg_hi:[0,1]
